# combination: residual-epilogue load hoist + adaLN DPP reductions + early chunk operand reads + pipelined hyena MFMA loops + unrolled RW scan, on top of v082
# speedup vs baseline: 1.0150x; 1.0061x over previous
.LBB0_405:
	s_or_b64 exec, exec, s[48:49]
	v_lshl_add_u64 v[2:3], v[2:3], 0, v[12:13]
	global_load_dwordx4 v[30:33], v[2:3], off
	global_load_dwordx4 v[34:37], v[2:3], off offset:1024
	global_load_dwordx4 v[38:41], v[2:3], off offset:2048
	s_nop 0
	global_load_dwordx4 v[2:5], v[2:3], off offset:3072
	s_nop 0
	global_load_dwordx4 v[42:45], v[8:9], off
	v_min_i32_e32 v0, 0x4000, v6
	v_ashrrev_i32_e32 v0, 11, v0
	v_mul_hi_i32_i24_e32 v21, 0x9000, v0
	v_mul_i32_i24_e32 v20, 0x9000, v0
	v_lshl_add_u64 v[20:21], s[14:15], 0, v[20:21]
	v_lshl_add_u64 v[22:23], v[20:21], 0, s[38:39]
	v_lshl_add_u64 v[46:47], v[22:23], 0, v[12:13]
	global_load_dwordx4 v[46:49], v[46:47], off
	v_lshl_add_u64 v[54:55], v[20:21], 0, v[12:13]
	global_load_dwordx4 v[50:53], v[54:55], off
	s_mov_b32 s4, s42
	s_waitcnt vmcnt(6)
	v_mov_b32_e32 v56, v31
	s_waitcnt vmcnt(5)
	v_mov_b32_e32 v57, v35
	v_mov_b32_e32 v20, v30
	v_mov_b32_e32 v21, v34
	s_waitcnt vmcnt(4)
	v_mov_b32_e32 v64, v39
	s_waitcnt vmcnt(3)
	v_mov_b32_e32 v65, v3
	v_pk_mul_f32 v[56:57], v[56:57], v[56:57]
	v_mov_b32_e32 v58, v32
	v_mov_b32_e32 v59, v36
	v_mov_b32_e32 v62, v38
	v_mov_b32_e32 v63, v2
	v_pk_mul_f32 v[64:65], v[64:65], v[64:65]
	v_pk_fma_f32 v[20:21], v[20:21], v[20:21], v[56:57]
	v_mov_b32_e32 v60, v33
	v_mov_b32_e32 v61, v37
	v_mov_b32_e32 v66, v40
	v_mov_b32_e32 v67, v4
	v_pk_fma_f32 v[56:57], v[62:63], v[62:63], v[64:65]
	v_pk_fma_f32 v[20:21], v[58:59], v[58:59], v[20:21]
	v_mov_b32_e32 v68, v41
	v_mov_b32_e32 v69, v5
	v_pk_fma_f32 v[56:57], v[66:67], v[66:67], v[56:57]
	v_pk_fma_f32 v[20:21], v[60:61], v[60:61], v[20:21]
	v_pk_fma_f32 v[56:57], v[68:69], v[68:69], v[56:57]
	v_add_f32_e32 v0, v20, v21
	v_add_f32_e32 v0, v0, v56
	v_add_f32_e32 v0, v0, v57
	ds_bpermute_b32 v20, v24, v0
	s_waitcnt vmcnt(2)
	v_mov_b32_e32 v57, v44
	v_mov_b32_e32 v44, v43
	v_mov_b32_e32 v43, v32
	s_waitcnt vmcnt(1)
	v_mov_b32_e32 v32, v46
	s_waitcnt lgkmcnt(0)
	v_add_f32_e32 v0, v0, v20
	ds_bpermute_b32 v20, v25, v0
	s_waitcnt vmcnt(0)
	v_mov_b32_e32 v59, v52
	v_mov_b32_e32 v52, v51
	v_mov_b32_e32 v58, v50
	v_mov_b32_e32 v50, v34
	s_waitcnt lgkmcnt(0)
	v_add_f32_e32 v0, v0, v20
	v_lshlrev_b64 v[20:21], 11, v[6:7]
	v_lshl_add_u64 v[20:21], v[10:11], 0, v[20:21]
	v_mov_b32_e32 v51, v36
	v_mov_b32_e32 v36, v35
	s_waitcnt lgkmcnt(0)
	s_nop 1
	v_add_f32_dpp v0, v0, v0 row_ror:8 row_mask:0xf bank_mask:0xf bound_ctrl:1
	v_mov_b32_e32 v56, v42
	v_mov_b32_e32 v42, v30
	v_mov_b32_e32 v30, v31
	v_mov_b32_e32 v31, v33
	s_waitcnt lgkmcnt(0)
	s_nop 1
	v_add_f32_dpp v0, v0, v0 row_ror:4 row_mask:0xf bank_mask:0xf bound_ctrl:1
	v_mov_b32_e32 v33, v48
	v_mov_b32_e32 v48, v47
	v_pk_add_f32 v[46:47], v[48:49], 1.0 op_sel_hi:[1,0]
	v_pk_add_f32 v[32:33], v[32:33], 1.0 op_sel_hi:[1,0]
	s_waitcnt lgkmcnt(0)
	s_nop 1
	v_add_f32_dpp v0, v0, v0 quad_perm:[2,3,0,1] row_mask:0xf bank_mask:0xf bound_ctrl:1
	s_waitcnt lgkmcnt(0)
	s_nop 1
	v_add_f32_dpp v0, v0, v0 quad_perm:[1,0,3,2] row_mask:0xf bank_mask:0xf bound_ctrl:1
	v_fmamk_f32 v0, v0, 0x3a800000, v174
	v_mul_f32_e32 v7, 0x4b800000, v0
	v_cmp_gt_f32_e32 vcc, s27, v0
	s_nop 1
	v_cndmask_b32_e32 v0, v0, v7, vcc
	v_rsq_f32_e32 v0, v0
	s_nop 0
	v_mul_f32_e32 v7, 0x45800000, v0
	v_cndmask_b32_e32 v0, v0, v7, vcc
	v_pk_mul_f32 v[30:31], v[30:31], v[0:1] op_sel_hi:[1,0]
	v_pk_mul_f32 v[42:43], v[42:43], v[0:1] op_sel_hi:[1,0]
	v_pk_mul_f32 v[30:31], v[44:45], v[30:31]
	v_pk_mul_f32 v[42:43], v[56:57], v[42:43]
	v_pk_fma_f32 v[30:31], v[46:47], v[30:31], v[52:53]
	v_pk_fma_f32 v[32:33], v[32:33], v[42:43], v[58:59]
	v_cvt_pk_bf16_f32 v7, v33, v31
	v_cvt_pk_bf16_f32 v32, v32, v30
	v_mov_b32_e32 v31, v7
	v_mov_b32_e32 v30, v32
	global_store_dwordx2 v[20:21], v[30:31], off
	global_load_dwordx4 v[30:33], v[8:9], off offset:1024
	v_lshl_add_u64 v[42:43], v[22:23], 0, v[14:15]
	global_load_dwordx4 v[42:45], v[42:43], off
	s_nop 0
	global_load_dwordx4 v[46:49], v[54:55], off offset:1024
	v_pk_mul_f32 v[34:35], v[50:51], v[0:1] op_sel_hi:[1,0]
	v_pk_mul_f32 v[36:37], v[36:37], v[0:1] op_sel_hi:[1,0]
	s_waitcnt vmcnt(2)
	v_mov_b32_e32 v50, v30
	v_mov_b32_e32 v51, v32
	s_waitcnt vmcnt(1)
	v_mov_b32_e32 v52, v42
	v_mov_b32_e32 v53, v44
	v_mov_b32_e32 v32, v31
	v_mov_b32_e32 v44, v43
	s_waitcnt vmcnt(0)
	v_mov_b32_e32 v56, v46
	v_mov_b32_e32 v57, v48
	v_mov_b32_e32 v48, v47
	v_pk_mul_f32 v[30:31], v[34:35], v[50:51]
	v_pk_add_f32 v[34:35], v[52:53], 1.0 op_sel_hi:[1,0]
	v_pk_mul_f32 v[32:33], v[36:37], v[32:33]
	v_pk_add_f32 v[36:37], v[44:45], 1.0 op_sel_hi:[1,0]
	v_pk_fma_f32 v[30:31], v[30:31], v[34:35], v[56:57]
	v_pk_fma_f32 v[32:33], v[32:33], v[36:37], v[48:49]
	v_cvt_pk_bf16_f32 v7, v31, v33
	v_cvt_pk_bf16_f32 v30, v30, v32
	v_mov_b32_e32 v31, v7
	global_store_dwordx2 v[20:21], v[30:31], off offset:512
	global_load_dwordx4 v[30:33], v[8:9], off offset:2048
	v_lshl_add_u64 v[34:35], v[22:23], 0, v[16:17]
	global_load_dwordx4 v[34:37], v[34:35], off
	s_nop 0
	global_load_dwordx4 v[42:45], v[54:55], off offset:2048
	v_mov_b32_e32 v46, v38
	v_mov_b32_e32 v47, v40
	v_mov_b32_e32 v38, v39
	v_mov_b32_e32 v39, v41
	v_pk_mul_f32 v[40:41], v[46:47], v[0:1] op_sel_hi:[1,0]
	v_pk_mul_f32 v[38:39], v[38:39], v[0:1] op_sel_hi:[1,0]
	v_lshl_add_u64 v[22:23], v[22:23], 0, v[18:19]
	s_waitcnt vmcnt(2)
	v_mov_b32_e32 v46, v30
	v_mov_b32_e32 v47, v32
	s_waitcnt vmcnt(1)
	v_mov_b32_e32 v48, v34
	v_mov_b32_e32 v49, v36
	v_mov_b32_e32 v32, v31
	v_mov_b32_e32 v36, v35
	s_waitcnt vmcnt(0)
	v_mov_b32_e32 v50, v42
	v_mov_b32_e32 v51, v44
	v_mov_b32_e32 v44, v43
	v_pk_mul_f32 v[30:31], v[40:41], v[46:47]
	v_pk_add_f32 v[34:35], v[48:49], 1.0 op_sel_hi:[1,0]
	v_pk_mul_f32 v[32:33], v[38:39], v[32:33]
	v_pk_add_f32 v[36:37], v[36:37], 1.0 op_sel_hi:[1,0]
	v_pk_fma_f32 v[30:31], v[30:31], v[34:35], v[50:51]
	v_pk_fma_f32 v[32:33], v[32:33], v[36:37], v[44:45]
	v_cvt_pk_bf16_f32 v7, v31, v33
	v_cvt_pk_bf16_f32 v30, v30, v32
	v_mov_b32_e32 v31, v7
	global_store_dwordx2 v[20:21], v[30:31], off offset:1024
	global_load_dwordx4 v[30:33], v[8:9], off offset:3072
	s_nop 0
	global_load_dwordx4 v[34:37], v[22:23], off
	global_load_dwordx4 v[38:41], v[54:55], off offset:3072
	v_mov_b32_e32 v22, v2
	v_mov_b32_e32 v23, v4
	v_mov_b32_e32 v4, v3
	v_pk_mul_f32 v[2:3], v[22:23], v[0:1] op_sel_hi:[1,0]
	v_pk_mul_f32 v[4:5], v[4:5], v[0:1] op_sel_hi:[1,0]
	s_waitcnt vmcnt(1)
	v_mov_b32_e32 v42, v34
	v_mov_b32_e32 v22, v30
	v_mov_b32_e32 v23, v32
	v_mov_b32_e32 v43, v36
	v_mov_b32_e32 v32, v31
	v_mov_b32_e32 v36, v35
	s_waitcnt vmcnt(0)
	v_mov_b32_e32 v44, v38
	v_mov_b32_e32 v45, v40
	v_mov_b32_e32 v40, v39
	v_pk_mul_f32 v[2:3], v[2:3], v[22:23]
	v_pk_add_f32 v[22:23], v[42:43], 1.0 op_sel_hi:[1,0]
	v_pk_mul_f32 v[4:5], v[4:5], v[32:33]
	v_pk_add_f32 v[30:31], v[36:37], 1.0 op_sel_hi:[1,0]
	v_pk_fma_f32 v[2:3], v[2:3], v[22:23], v[44:45]
	v_pk_fma_f32 v[4:5], v[4:5], v[30:31], v[40:41]
	v_cvt_pk_bf16_f32 v0, v3, v5
	v_and_b32_sdwa v23, v4, v177 dst_sel:DWORD dst_unused:UNUSED_PAD src0_sel:WORD_1 src1_sel:DWORD
	v_and_b32_sdwa v7, v2, v177 dst_sel:DWORD dst_unused:UNUSED_PAD src0_sel:WORD_1 src1_sel:DWORD
	v_add3_u32 v4, v4, v23, s28
	v_add3_u32 v2, v2, v7, s28
	v_and_b32_e32 v4, 0xffff0000, v4
	v_mov_b32_e32 v3, v0
	v_or_b32_sdwa v2, v4, v2 dst_sel:DWORD dst_unused:UNUSED_PAD src0_sel:DWORD src1_sel:WORD_1
	global_store_dwordx2 v[20:21], v[2:3], off offset:1536
	s_nop 0
	v_lshl_add_u32 v6, s4, 3, v6
	v_cmp_lt_i32_e32 vcc, s29, v6
	s_or_b64 s[46:47], vcc, s[46:47]
	s_andn2_b64 exec, exec, s[46:47]
	s_cbranch_execz .LBB0_410

.LBB0_604:
	s_or_b64 exec, exec, s[46:47]
	v_lshl_add_u64 v[2:3], v[2:3], 0, v[0:1]
	global_load_dwordx4 v[36:39], v[2:3], off
	global_load_dwordx4 v[40:43], v[2:3], off offset:1024
	global_load_dwordx4 v[44:47], v[2:3], off offset:2048
	s_nop 0
	global_load_dwordx4 v[2:5], v[2:3], off offset:3072
	s_nop 0
	global_load_dwordx4 v[48:51], v[8:9], off
	global_load_dwordx4 v[78:81], v[10:11], off
	global_load_dwordx4 v[90:93], v[12:13], off
	global_load_dwordx4 v[102:105], v[14:15], off
	v_min_i32_e32 v19, 0x4000, v6
	v_ashrrev_i32_e32 v19, 11, v19
	v_mul_hi_i32_i24_e32 v25, 0x9000, v19
	v_mul_i32_i24_e32 v24, 0x9000, v19
	v_lshl_add_u64 v[24:25], s[16:17], 0, v[24:25]
	v_lshl_add_u64 v[26:27], v[24:25], 0, s[38:39]
	v_lshl_add_u64 v[28:29], v[26:27], 0, v[0:1]
	global_load_dwordx4 v[52:55], v[28:29], off
	global_load_dwordx4 v[82:85], v[28:29], off offset:1024
	global_load_dwordx4 v[94:97], v[28:29], off offset:2048
	global_load_dwordx4 v[106:109], v[28:29], off offset:3072
	v_lshl_add_u64 v[28:29], v[24:25], 0, v[0:1]
	global_load_dwordx4 v[56:59], v[28:29], off
	global_load_dwordx4 v[86:89], v[28:29], off offset:1024
	global_load_dwordx4 v[98:101], v[28:29], off offset:2048
	global_load_dwordx4 v[110:113], v[28:29], off offset:3072
	s_mov_b32 s4, s42
	s_waitcnt vmcnt(15)
	v_mov_b32_e32 v60, v37
	s_waitcnt vmcnt(14)
	v_mov_b32_e32 v61, v41
	v_mov_b32_e32 v24, v36
	v_mov_b32_e32 v25, v40
	s_waitcnt vmcnt(13)
	v_mov_b32_e32 v68, v45
	s_waitcnt vmcnt(12)
	v_mov_b32_e32 v69, v3
	v_pk_mul_f32 v[60:61], v[60:61], v[60:61]
	v_mov_b32_e32 v62, v38
	v_mov_b32_e32 v63, v42
	v_mov_b32_e32 v66, v44
	v_mov_b32_e32 v67, v2
	v_pk_mul_f32 v[68:69], v[68:69], v[68:69]
	v_pk_fma_f32 v[24:25], v[24:25], v[24:25], v[60:61]
	v_mov_b32_e32 v64, v39
	v_mov_b32_e32 v65, v43
	v_mov_b32_e32 v70, v46
	v_mov_b32_e32 v71, v4
	v_pk_fma_f32 v[60:61], v[66:67], v[66:67], v[68:69]
	v_pk_fma_f32 v[24:25], v[62:63], v[62:63], v[24:25]
	v_mov_b32_e32 v72, v47
	v_mov_b32_e32 v73, v5
	v_pk_fma_f32 v[60:61], v[70:71], v[70:71], v[60:61]
	v_pk_fma_f32 v[24:25], v[64:65], v[64:65], v[24:25]
	v_pk_fma_f32 v[60:61], v[72:73], v[72:73], v[60:61]
	v_add_f32_e32 v19, v24, v25
	v_add_f32_e32 v19, v19, v60
	v_add_f32_e32 v19, v19, v61
	ds_bpermute_b32 v21, v30, v19
	v_lshlrev_b64 v[24:25], 11, v[6:7]
	s_waitcnt vmcnt(11)
	v_mov_b32_e32 v60, v48
	v_mov_b32_e32 v48, v36
	v_mov_b32_e32 v36, v37
	s_waitcnt lgkmcnt(0)
	v_add_f32_e32 v19, v19, v21
	ds_bpermute_b32 v21, v31, v19
	v_mov_b32_e32 v37, v39
	s_waitcnt vmcnt(3)
	v_mov_b32_e32 v62, v56
	v_mov_b32_e32 v61, v50
	v_mov_b32_e32 v50, v49
	s_waitcnt lgkmcnt(0)
	v_add_f32_e32 v21, v19, v21
	v_mov_b32_e32 v49, v38
	v_mov_b32_e32 v39, v54
	v_mov_b32_e32 v54, v53
	v_mov_b32_e32 v38, v52
	s_waitcnt lgkmcnt(0)
	s_nop 1
	v_add_f32_dpp v7, v21, v21 row_ror:8 row_mask:0xf bank_mask:0xf bound_ctrl:1
	v_mov_b32_e32 v63, v58
	v_mov_b32_e32 v58, v57
	v_pk_add_f32 v[52:53], v[54:55], 1.0 op_sel_hi:[1,0]
	v_pk_add_f32 v[38:39], v[38:39], 1.0 op_sel_hi:[1,0]
	s_waitcnt lgkmcnt(0)
	s_nop 1
	v_add_f32_dpp v7, v7, v7 row_ror:4 row_mask:0xf bank_mask:0xf bound_ctrl:1
	v_lshl_add_u64 v[24:25], v[16:17], 0, v[24:25]
	v_mov_b32_e32 v19, v1
	s_waitcnt lgkmcnt(0)
	s_nop 1
	v_add_f32_dpp v7, v7, v7 quad_perm:[2,3,0,1] row_mask:0xf bank_mask:0xf bound_ctrl:1
	s_waitcnt lgkmcnt(0)
	s_nop 1
	v_add_f32_dpp v7, v7, v7 quad_perm:[1,0,3,2] row_mask:0xf bank_mask:0xf bound_ctrl:1
	v_fmamk_f32 v7, v7, 0x3a800000, v174
	v_mul_f32_e32 v21, 0x4b800000, v7
	v_cmp_gt_f32_e32 vcc, s27, v7
	s_nop 1
	v_cndmask_b32_e32 v7, v7, v21, vcc
	v_rsq_f32_e32 v7, v7
	s_nop 0
	v_mul_f32_e32 v21, 0x45800000, v7
	v_cndmask_b32_e32 v56, v7, v21, vcc
	v_pk_mul_f32 v[36:37], v[36:37], v[56:57] op_sel_hi:[1,0]
	v_pk_mul_f32 v[48:49], v[48:49], v[56:57] op_sel_hi:[1,0]
	v_pk_mul_f32 v[36:37], v[50:51], v[36:37]
	v_pk_mul_f32 v[48:49], v[60:61], v[48:49]
	v_pk_fma_f32 v[36:37], v[52:53], v[36:37], v[58:59]
	v_pk_fma_f32 v[38:39], v[38:39], v[48:49], v[62:63]
	v_cvt_pk_bf16_f32 v21, v38, v36
	v_cvt_pk_bf16_f32 v37, v39, v37
	v_mov_b32_e32 v36, v21
	global_store_dwordx2 v[24:25], v[36:37], off
	v_lshl_add_u64 v[48:49], v[26:27], 0, v[18:19]
	s_waitcnt vmcnt(1)
	v_mov_b32_e32 v52, v86
	v_mov_b32_e32 v53, v87
	v_mov_b32_e32 v54, v88
	v_mov_b32_e32 v55, v89
	v_mov_b32_e32 v48, v82
	v_mov_b32_e32 v49, v83
	v_mov_b32_e32 v50, v84
	v_mov_b32_e32 v51, v85
	v_mov_b32_e32 v36, v78
	v_mov_b32_e32 v37, v79
	v_mov_b32_e32 v38, v80
	v_mov_b32_e32 v39, v81
	v_mov_b32_e32 v58, v40
	v_mov_b32_e32 v59, v42
	v_mov_b32_e32 v42, v41
	v_pk_mul_f32 v[40:41], v[58:59], v[56:57] op_sel_hi:[1,0]
	v_pk_mul_f32 v[42:43], v[42:43], v[56:57] op_sel_hi:[1,0]
	v_mov_b32_e32 v21, v1
	v_mov_b32_e32 v58, v36
	v_mov_b32_e32 v59, v38
	v_mov_b32_e32 v60, v48
	v_mov_b32_e32 v61, v50
	v_mov_b32_e32 v38, v37
	v_mov_b32_e32 v50, v49
	v_mov_b32_e32 v62, v52
	v_mov_b32_e32 v63, v54
	v_mov_b32_e32 v54, v53
	v_pk_mul_f32 v[36:37], v[40:41], v[58:59]
	v_pk_add_f32 v[40:41], v[60:61], 1.0 op_sel_hi:[1,0]
	v_pk_mul_f32 v[38:39], v[42:43], v[38:39]
	v_pk_add_f32 v[42:43], v[50:51], 1.0 op_sel_hi:[1,0]
	v_pk_fma_f32 v[36:37], v[36:37], v[40:41], v[62:63]
	v_pk_fma_f32 v[38:39], v[38:39], v[42:43], v[54:55]
	v_cvt_pk_bf16_f32 v19, v36, v38
	v_cvt_pk_bf16_f32 v37, v37, v39
	v_mov_b32_e32 v36, v19
	global_store_dwordx2 v[24:25], v[36:37], off offset:512
	v_lshl_add_u64 v[40:41], v[26:27], 0, v[20:21]
	v_mov_b32_e32 v48, v98
	v_mov_b32_e32 v49, v99
	v_mov_b32_e32 v50, v100
	v_mov_b32_e32 v51, v101
	v_mov_b32_e32 v40, v94
	v_mov_b32_e32 v41, v95
	v_mov_b32_e32 v42, v96
	v_mov_b32_e32 v43, v97
	v_mov_b32_e32 v36, v90
	v_mov_b32_e32 v37, v91
	v_mov_b32_e32 v38, v92
	v_mov_b32_e32 v39, v93
	v_mov_b32_e32 v52, v44
	v_mov_b32_e32 v53, v46
	v_mov_b32_e32 v44, v45
	v_mov_b32_e32 v45, v47
	v_pk_mul_f32 v[46:47], v[52:53], v[56:57] op_sel_hi:[1,0]
	v_pk_mul_f32 v[44:45], v[44:45], v[56:57] op_sel_hi:[1,0]
	v_mov_b32_e32 v23, v1
	v_lshl_add_u64 v[26:27], v[26:27], 0, v[22:23]
	v_mov_b32_e32 v52, v36
	v_mov_b32_e32 v53, v38
	v_mov_b32_e32 v54, v40
	v_mov_b32_e32 v55, v42
	v_mov_b32_e32 v38, v37
	v_mov_b32_e32 v42, v41
	v_mov_b32_e32 v58, v48
	v_mov_b32_e32 v59, v50
	v_mov_b32_e32 v50, v49
	v_pk_mul_f32 v[36:37], v[46:47], v[52:53]
	v_pk_add_f32 v[40:41], v[54:55], 1.0 op_sel_hi:[1,0]
	v_pk_mul_f32 v[38:39], v[44:45], v[38:39]
	v_pk_add_f32 v[42:43], v[42:43], 1.0 op_sel_hi:[1,0]
	v_pk_fma_f32 v[36:37], v[36:37], v[40:41], v[58:59]
	v_pk_fma_f32 v[38:39], v[38:39], v[42:43], v[50:51]
	v_cvt_pk_bf16_f32 v19, v36, v38
	v_cvt_pk_bf16_f32 v37, v37, v39
	v_mov_b32_e32 v36, v19
	global_store_dwordx2 v[24:25], v[36:37], off offset:1024
	v_mov_b32_e32 v26, v110
	v_mov_b32_e32 v27, v111
	v_mov_b32_e32 v28, v112
	v_mov_b32_e32 v29, v113
	v_mov_b32_e32 v40, v106
	v_mov_b32_e32 v41, v107
	v_mov_b32_e32 v42, v108
	v_mov_b32_e32 v43, v109
	v_mov_b32_e32 v36, v102
	v_mov_b32_e32 v37, v103
	v_mov_b32_e32 v38, v104
	v_mov_b32_e32 v39, v105
	v_mov_b32_e32 v44, v2
	v_mov_b32_e32 v45, v4
	v_mov_b32_e32 v4, v3
	v_pk_mul_f32 v[2:3], v[44:45], v[56:57] op_sel_hi:[1,0]
	v_pk_mul_f32 v[4:5], v[4:5], v[56:57] op_sel_hi:[1,0]
	v_mov_b32_e32 v47, v42
	v_mov_b32_e32 v45, v38
	v_mov_b32_e32 v38, v37
	v_mov_b32_e32 v42, v41
	v_mov_b32_e32 v44, v36
	v_mov_b32_e32 v46, v40
	v_mov_b32_e32 v49, v28
	v_mov_b32_e32 v28, v27
	v_pk_mul_f32 v[4:5], v[4:5], v[38:39]
	v_pk_add_f32 v[36:37], v[42:43], 1.0 op_sel_hi:[1,0]
	v_mov_b32_e32 v48, v26
	v_pk_mul_f32 v[2:3], v[2:3], v[44:45]
	v_pk_add_f32 v[26:27], v[46:47], 1.0 op_sel_hi:[1,0]
	v_pk_fma_f32 v[4:5], v[4:5], v[36:37], v[28:29]
	v_pk_fma_f32 v[2:3], v[2:3], v[26:27], v[48:49]
	v_and_b32_sdwa v21, v5, v177 dst_sel:DWORD dst_unused:UNUSED_PAD src0_sel:WORD_1 src1_sel:DWORD
	v_and_b32_sdwa v23, v4, v177 dst_sel:DWORD dst_unused:UNUSED_PAD src0_sel:WORD_1 src1_sel:DWORD
	v_and_b32_sdwa v7, v3, v177 dst_sel:DWORD dst_unused:UNUSED_PAD src0_sel:WORD_1 src1_sel:DWORD
	v_and_b32_sdwa v19, v2, v177 dst_sel:DWORD dst_unused:UNUSED_PAD src0_sel:WORD_1 src1_sel:DWORD
	v_add3_u32 v5, v5, v21, s28
	v_add3_u32 v4, v4, v23, s28
	v_add3_u32 v2, v2, v19, s28
	v_add3_u32 v3, v3, v7, s28
	v_and_b32_e32 v5, 0xffff0000, v5
	v_and_b32_e32 v4, 0xffff0000, v4
	v_or_b32_sdwa v3, v5, v3 dst_sel:DWORD dst_unused:UNUSED_PAD src0_sel:DWORD src1_sel:WORD_1
	v_or_b32_sdwa v2, v4, v2 dst_sel:DWORD dst_unused:UNUSED_PAD src0_sel:DWORD src1_sel:WORD_1
	global_store_dwordx2 v[24:25], v[2:3], off offset:1536
	s_nop 0
	v_lshl_add_u32 v6, s4, 3, v6
	v_cmp_lt_i32_e32 vcc, s29, v6
	s_or_b64 s[18:19], vcc, s[18:19]
	s_andn2_b64 exec, exec, s[18:19]
	s_cbranch_execz .LBB0_609

.LBB0_1379:
	s_or_b64 exec, exec, s[46:47]
	v_lshl_add_u64 v[2:3], v[2:3], 0, v[0:1]
	global_load_dwordx4 v[36:39], v[2:3], off
	global_load_dwordx4 v[40:43], v[2:3], off offset:1024
	global_load_dwordx4 v[44:47], v[2:3], off offset:2048
	s_nop 0
	global_load_dwordx4 v[2:5], v[2:3], off offset:3072
	s_nop 0
	global_load_dwordx4 v[48:51], v[8:9], off
	global_load_dwordx4 v[78:81], v[10:11], off
	global_load_dwordx4 v[90:93], v[12:13], off
	global_load_dwordx4 v[102:105], v[14:15], off
	v_min_i32_e32 v19, 0x4000, v6
	v_ashrrev_i32_e32 v19, 11, v19
	v_mul_hi_i32_i24_e32 v25, 0x9000, v19
	v_mul_i32_i24_e32 v24, 0x9000, v19
	v_lshl_add_u64 v[24:25], s[16:17], 0, v[24:25]
	v_lshl_add_u64 v[26:27], v[24:25], 0, s[38:39]
	v_lshl_add_u64 v[28:29], v[26:27], 0, v[0:1]
	global_load_dwordx4 v[52:55], v[28:29], off
	global_load_dwordx4 v[82:85], v[28:29], off offset:1024
	global_load_dwordx4 v[94:97], v[28:29], off offset:2048
	global_load_dwordx4 v[106:109], v[28:29], off offset:3072
	v_lshl_add_u64 v[28:29], v[24:25], 0, v[0:1]
	global_load_dwordx4 v[56:59], v[28:29], off
	global_load_dwordx4 v[86:89], v[28:29], off offset:1024
	global_load_dwordx4 v[98:101], v[28:29], off offset:2048
	global_load_dwordx4 v[110:113], v[28:29], off offset:3072
	s_mov_b32 s2, s42
	s_waitcnt vmcnt(15)
	v_mov_b32_e32 v60, v37
	s_waitcnt vmcnt(14)
	v_mov_b32_e32 v61, v41
	v_mov_b32_e32 v24, v36
	v_mov_b32_e32 v25, v40
	s_waitcnt vmcnt(13)
	v_mov_b32_e32 v68, v45
	s_waitcnt vmcnt(12)
	v_mov_b32_e32 v69, v3
	v_pk_mul_f32 v[60:61], v[60:61], v[60:61]
	v_mov_b32_e32 v62, v38
	v_mov_b32_e32 v63, v42
	v_mov_b32_e32 v66, v44
	v_mov_b32_e32 v67, v2
	v_pk_mul_f32 v[68:69], v[68:69], v[68:69]
	v_pk_fma_f32 v[24:25], v[24:25], v[24:25], v[60:61]
	v_mov_b32_e32 v64, v39
	v_mov_b32_e32 v65, v43
	v_mov_b32_e32 v70, v46
	v_mov_b32_e32 v71, v4
	v_pk_fma_f32 v[60:61], v[66:67], v[66:67], v[68:69]
	v_pk_fma_f32 v[24:25], v[62:63], v[62:63], v[24:25]
	v_mov_b32_e32 v72, v47
	v_mov_b32_e32 v73, v5
	v_pk_fma_f32 v[60:61], v[70:71], v[70:71], v[60:61]
	v_pk_fma_f32 v[24:25], v[64:65], v[64:65], v[24:25]
	v_pk_fma_f32 v[60:61], v[72:73], v[72:73], v[60:61]
	v_add_f32_e32 v19, v24, v25
	v_add_f32_e32 v19, v19, v60
	v_add_f32_e32 v19, v19, v61
	ds_bpermute_b32 v21, v30, v19
	v_lshlrev_b64 v[24:25], 11, v[6:7]
	s_waitcnt vmcnt(11)
	v_mov_b32_e32 v60, v48
	v_mov_b32_e32 v48, v36
	v_mov_b32_e32 v36, v37
	s_waitcnt lgkmcnt(0)
	v_add_f32_e32 v19, v19, v21
	ds_bpermute_b32 v21, v31, v19
	v_mov_b32_e32 v37, v39
	s_waitcnt vmcnt(3)
	v_mov_b32_e32 v62, v56
	v_mov_b32_e32 v61, v50
	v_mov_b32_e32 v50, v49
	s_waitcnt lgkmcnt(0)
	v_add_f32_e32 v21, v19, v21
	v_mov_b32_e32 v49, v38
	v_mov_b32_e32 v39, v54
	v_mov_b32_e32 v54, v53
	v_mov_b32_e32 v38, v52
	s_waitcnt lgkmcnt(0)
	s_nop 1
	v_add_f32_dpp v7, v21, v21 row_ror:8 row_mask:0xf bank_mask:0xf bound_ctrl:1
	v_mov_b32_e32 v63, v58
	v_mov_b32_e32 v58, v57
	v_pk_add_f32 v[52:53], v[54:55], 1.0 op_sel_hi:[1,0]
	v_pk_add_f32 v[38:39], v[38:39], 1.0 op_sel_hi:[1,0]
	s_waitcnt lgkmcnt(0)
	s_nop 1
	v_add_f32_dpp v7, v7, v7 row_ror:4 row_mask:0xf bank_mask:0xf bound_ctrl:1
	v_lshl_add_u64 v[24:25], v[16:17], 0, v[24:25]
	v_mov_b32_e32 v19, v1
	s_waitcnt lgkmcnt(0)
	s_nop 1
	v_add_f32_dpp v7, v7, v7 quad_perm:[2,3,0,1] row_mask:0xf bank_mask:0xf bound_ctrl:1
	s_waitcnt lgkmcnt(0)
	s_nop 1
	v_add_f32_dpp v7, v7, v7 quad_perm:[1,0,3,2] row_mask:0xf bank_mask:0xf bound_ctrl:1
	v_fmamk_f32 v7, v7, 0x3a800000, v174
	v_mul_f32_e32 v21, 0x4b800000, v7
	v_cmp_gt_f32_e32 vcc, s27, v7
	s_nop 1
	v_cndmask_b32_e32 v7, v7, v21, vcc
	v_rsq_f32_e32 v7, v7
	s_nop 0
	v_mul_f32_e32 v21, 0x45800000, v7
	v_cndmask_b32_e32 v56, v7, v21, vcc
	v_pk_mul_f32 v[36:37], v[36:37], v[56:57] op_sel_hi:[1,0]
	v_pk_mul_f32 v[48:49], v[48:49], v[56:57] op_sel_hi:[1,0]
	v_pk_mul_f32 v[36:37], v[50:51], v[36:37]
	v_pk_mul_f32 v[48:49], v[60:61], v[48:49]
	v_pk_fma_f32 v[36:37], v[52:53], v[36:37], v[58:59]
	v_pk_fma_f32 v[38:39], v[38:39], v[48:49], v[62:63]
	v_cvt_pk_bf16_f32 v21, v38, v36
	v_cvt_pk_bf16_f32 v37, v39, v37
	v_mov_b32_e32 v36, v21
	global_store_dwordx2 v[24:25], v[36:37], off
	v_lshl_add_u64 v[48:49], v[26:27], 0, v[18:19]
	s_waitcnt vmcnt(1)
	v_mov_b32_e32 v52, v86
	v_mov_b32_e32 v53, v87
	v_mov_b32_e32 v54, v88
	v_mov_b32_e32 v55, v89
	v_mov_b32_e32 v48, v82
	v_mov_b32_e32 v49, v83
	v_mov_b32_e32 v50, v84
	v_mov_b32_e32 v51, v85
	v_mov_b32_e32 v36, v78
	v_mov_b32_e32 v37, v79
	v_mov_b32_e32 v38, v80
	v_mov_b32_e32 v39, v81
	v_mov_b32_e32 v58, v40
	v_mov_b32_e32 v59, v42
	v_mov_b32_e32 v42, v41
	v_pk_mul_f32 v[40:41], v[58:59], v[56:57] op_sel_hi:[1,0]
	v_pk_mul_f32 v[42:43], v[42:43], v[56:57] op_sel_hi:[1,0]
	v_mov_b32_e32 v21, v1
	v_mov_b32_e32 v58, v36
	v_mov_b32_e32 v59, v38
	v_mov_b32_e32 v60, v48
	v_mov_b32_e32 v61, v50
	v_mov_b32_e32 v38, v37
	v_mov_b32_e32 v50, v49
	v_mov_b32_e32 v62, v52
	v_mov_b32_e32 v63, v54
	v_mov_b32_e32 v54, v53
	v_pk_mul_f32 v[36:37], v[40:41], v[58:59]
	v_pk_add_f32 v[40:41], v[60:61], 1.0 op_sel_hi:[1,0]
	v_pk_mul_f32 v[38:39], v[42:43], v[38:39]
	v_pk_add_f32 v[42:43], v[50:51], 1.0 op_sel_hi:[1,0]
	v_pk_fma_f32 v[36:37], v[36:37], v[40:41], v[62:63]
	v_pk_fma_f32 v[38:39], v[38:39], v[42:43], v[54:55]
	v_cvt_pk_bf16_f32 v19, v36, v38
	v_cvt_pk_bf16_f32 v37, v37, v39
	v_mov_b32_e32 v36, v19
	global_store_dwordx2 v[24:25], v[36:37], off offset:512
	v_lshl_add_u64 v[40:41], v[26:27], 0, v[20:21]
	v_mov_b32_e32 v48, v98
	v_mov_b32_e32 v49, v99
	v_mov_b32_e32 v50, v100
	v_mov_b32_e32 v51, v101
	v_mov_b32_e32 v40, v94
	v_mov_b32_e32 v41, v95
	v_mov_b32_e32 v42, v96
	v_mov_b32_e32 v43, v97
	v_mov_b32_e32 v36, v90
	v_mov_b32_e32 v37, v91
	v_mov_b32_e32 v38, v92
	v_mov_b32_e32 v39, v93
	v_mov_b32_e32 v52, v44
	v_mov_b32_e32 v53, v46
	v_mov_b32_e32 v44, v45
	v_mov_b32_e32 v45, v47
	v_pk_mul_f32 v[46:47], v[52:53], v[56:57] op_sel_hi:[1,0]
	v_pk_mul_f32 v[44:45], v[44:45], v[56:57] op_sel_hi:[1,0]
	v_mov_b32_e32 v23, v1
	v_lshl_add_u64 v[26:27], v[26:27], 0, v[22:23]
	v_mov_b32_e32 v52, v36
	v_mov_b32_e32 v53, v38
	v_mov_b32_e32 v54, v40
	v_mov_b32_e32 v55, v42
	v_mov_b32_e32 v38, v37
	v_mov_b32_e32 v42, v41
	v_mov_b32_e32 v58, v48
	v_mov_b32_e32 v59, v50
	v_mov_b32_e32 v50, v49
	v_pk_mul_f32 v[36:37], v[46:47], v[52:53]
	v_pk_add_f32 v[40:41], v[54:55], 1.0 op_sel_hi:[1,0]
	v_pk_mul_f32 v[38:39], v[44:45], v[38:39]
	v_pk_add_f32 v[42:43], v[42:43], 1.0 op_sel_hi:[1,0]
	v_pk_fma_f32 v[36:37], v[36:37], v[40:41], v[58:59]
	v_pk_fma_f32 v[38:39], v[38:39], v[42:43], v[50:51]
	v_cvt_pk_bf16_f32 v19, v36, v38
	v_cvt_pk_bf16_f32 v37, v37, v39
	v_mov_b32_e32 v36, v19
	global_store_dwordx2 v[24:25], v[36:37], off offset:1024
	v_mov_b32_e32 v26, v110
	v_mov_b32_e32 v27, v111
	v_mov_b32_e32 v28, v112
	v_mov_b32_e32 v29, v113
	v_mov_b32_e32 v40, v106
	v_mov_b32_e32 v41, v107
	v_mov_b32_e32 v42, v108
	v_mov_b32_e32 v43, v109
	v_mov_b32_e32 v36, v102
	v_mov_b32_e32 v37, v103
	v_mov_b32_e32 v38, v104
	v_mov_b32_e32 v39, v105
	v_mov_b32_e32 v44, v2
	v_mov_b32_e32 v45, v4
	v_mov_b32_e32 v4, v3
	v_pk_mul_f32 v[2:3], v[44:45], v[56:57] op_sel_hi:[1,0]
	v_pk_mul_f32 v[4:5], v[4:5], v[56:57] op_sel_hi:[1,0]
	v_mov_b32_e32 v47, v42
	v_mov_b32_e32 v45, v38
	v_mov_b32_e32 v38, v37
	v_mov_b32_e32 v42, v41
	v_mov_b32_e32 v44, v36
	v_mov_b32_e32 v46, v40
	v_mov_b32_e32 v49, v28
	v_mov_b32_e32 v28, v27
	v_pk_mul_f32 v[4:5], v[4:5], v[38:39]
	v_pk_add_f32 v[36:37], v[42:43], 1.0 op_sel_hi:[1,0]
	v_mov_b32_e32 v48, v26
	v_pk_mul_f32 v[2:3], v[2:3], v[44:45]
	v_pk_add_f32 v[26:27], v[46:47], 1.0 op_sel_hi:[1,0]
	v_pk_fma_f32 v[4:5], v[4:5], v[36:37], v[28:29]
	v_pk_fma_f32 v[2:3], v[2:3], v[26:27], v[48:49]
	v_cvt_pk_bf16_f32 v3, v3, v5
	v_and_b32_sdwa v23, v4, v177 dst_sel:DWORD dst_unused:UNUSED_PAD src0_sel:WORD_1 src1_sel:DWORD
	v_and_b32_sdwa v19, v2, v177 dst_sel:DWORD dst_unused:UNUSED_PAD src0_sel:WORD_1 src1_sel:DWORD
	v_add3_u32 v4, v4, v23, s28
	v_add3_u32 v2, v2, v19, s28
	v_and_b32_e32 v4, 0xffff0000, v4
	v_or_b32_sdwa v2, v4, v2 dst_sel:DWORD dst_unused:UNUSED_PAD src0_sel:DWORD src1_sel:WORD_1
	global_store_dwordx2 v[24:25], v[2:3], off offset:1536
	s_nop 0
	v_lshl_add_u32 v6, s2, 3, v6
	v_cmp_le_i32_e32 vcc, s11, v6
	s_or_b64 s[18:19], vcc, s[18:19]
	s_andn2_b64 exec, exec, s[18:19]
	s_cbranch_execz .LBB0_1384
